# grid barrier: all workgroups poll the top generation word directly, per-XCD forward hop removed
# speedup vs baseline: 1.0247x; 1.0002x over previous
.LBB0_79:
	s_or_b64 exec, exec, s[10:11]
	v_cvt_f32_u32_e32 v4, v2
	s_waitcnt vmcnt(0)
	v_readfirstlane_b32 s3, v3
	v_sub_u32_e32 v3, 0, v2
	v_rcp_iflag_f32_e32 v4, v4
	v_add_u32_e32 v5, s3, v1
	v_mul_f32_e32 v4, 0x4f7ffffe, v4
	v_cvt_u32_f32_e32 v4, v4
	v_mul_lo_u32 v1, v3, v4
	v_mul_hi_u32 v1, v4, v1
	v_add_u32_e32 v1, v4, v1
	v_mul_hi_u32 v1, v5, v1
	v_mul_lo_u32 v3, v1, v2
	v_sub_u32_e32 v3, v5, v3
	v_add_u32_e32 v4, 1, v1
	v_cmp_ge_u32_e32 vcc, v3, v2
	s_nop 1
	v_cndmask_b32_e32 v1, v1, v4, vcc
	v_sub_u32_e32 v4, v3, v2
	v_cndmask_b32_e32 v3, v3, v4, vcc
	v_add_u32_e32 v4, 1, v1
	v_cmp_ge_u32_e32 vcc, v3, v2
	v_add_u32_e32 v3, 1, v5
	s_nop 0
	v_cndmask_b32_e32 v1, v1, v4, vcc
	v_mul_lo_u32 v4, v2, v1
	v_add_u32_e32 v2, v4, v2
	v_cmp_ne_u32_e32 vcc, v3, v2
	s_and_saveexec_b64 s[8:9], vcc
	s_xor_b64 s[8:9], exec, s[8:9]
	s_cbranch_execz .LBB0_93
	s_waitcnt lgkmcnt(0)
	v_mov_b32_e32 v0, 0x7000
	global_load_dword v0, v0, s[22:23] offset:1280 sc1
	s_add_u32 s34, s22, 0x7500
	s_addc_u32 s35, s23, 0
	s_waitcnt vmcnt(0)
	v_cmp_eq_u32_e32 vcc, v0, v1
	s_and_saveexec_b64 s[10:11], vcc
	s_cbranch_execz .LBB0_92
	s_add_u32 s14, s22, 0x4200
	s_addc_u32 s15, s23, 0
	s_mov_b32 s3, 1
	s_mov_b64 s[38:39], 0
	v_mov_b32_e32 v0, 0
	s_branch .LBB0_83

.LBB0_110:
	s_or_b64 exec, exec, s[8:9]
	s_mov_b64 s[8:9], exec
	v_mbcnt_lo_u32_b32 v0, s8, 0
	v_mbcnt_hi_u32_b32 v0, s9, v0
	v_cmp_eq_u32_e32 vcc, 0, v0
	s_waitcnt vmcnt(0)
	buffer_inv sc1
	s_and_saveexec_b64 s[10:11], vcc
	s_cbranch_execz .LBB0_112
	s_bcnt1_i32_b64 s3, s[8:9]
	v_mov_b32_e32 v0, 0x2000
	v_mov_b32_e32 v1, s3
.LBB0_112:
	s_or_b64 exec, exec, s[10:11]
	s_waitcnt vmcnt(0)

.LBB0_293:
	s_or_b64 exec, exec, s[10:11]
	v_cvt_f32_u32_e32 v4, v2
	s_waitcnt vmcnt(0)
	v_readfirstlane_b32 s3, v3
	v_sub_u32_e32 v3, 0, v2
	v_rcp_iflag_f32_e32 v4, v4
	v_add_u32_e32 v5, s3, v1
	v_mul_f32_e32 v4, 0x4f7ffffe, v4
	v_cvt_u32_f32_e32 v4, v4
	v_mul_lo_u32 v1, v3, v4
	v_mul_hi_u32 v1, v4, v1
	v_add_u32_e32 v1, v4, v1
	v_mul_hi_u32 v1, v5, v1
	v_mul_lo_u32 v3, v1, v2
	v_sub_u32_e32 v3, v5, v3
	v_add_u32_e32 v4, 1, v1
	v_cmp_ge_u32_e32 vcc, v3, v2
	s_nop 1
	v_cndmask_b32_e32 v1, v1, v4, vcc
	v_sub_u32_e32 v4, v3, v2
	v_cndmask_b32_e32 v3, v3, v4, vcc
	v_add_u32_e32 v4, 1, v1
	v_cmp_ge_u32_e32 vcc, v3, v2
	v_add_u32_e32 v3, 1, v5
	s_nop 0
	v_cndmask_b32_e32 v1, v1, v4, vcc
	v_mul_lo_u32 v4, v2, v1
	v_add_u32_e32 v2, v4, v2
	v_cmp_ne_u32_e32 vcc, v3, v2
	s_and_saveexec_b64 s[8:9], vcc
	s_xor_b64 s[8:9], exec, s[8:9]
	s_cbranch_execz .LBB0_307
	s_waitcnt lgkmcnt(0)
	v_mov_b32_e32 v0, 0x7000
	global_load_dword v0, v0, s[22:23] offset:1280 sc1
	s_add_u32 s38, s22, 0x7500
	s_addc_u32 s39, s23, 0
	s_waitcnt vmcnt(0)
	v_cmp_eq_u32_e32 vcc, v0, v1
	s_and_saveexec_b64 s[10:11], vcc
	s_cbranch_execz .LBB0_306
	s_add_u32 s14, s22, 0x4200
	s_addc_u32 s15, s23, 0
	s_mov_b32 s3, 1
	s_mov_b64 s[40:41], 0
	v_mov_b32_e32 v0, 0
	s_branch .LBB0_297

.LBB0_324:
	s_or_b64 exec, exec, s[8:9]
	s_mov_b64 s[8:9], exec
	v_mbcnt_lo_u32_b32 v0, s8, 0
	v_mbcnt_hi_u32_b32 v0, s9, v0
	v_cmp_eq_u32_e32 vcc, 0, v0
	s_waitcnt vmcnt(0)
	buffer_inv sc1
	s_and_saveexec_b64 s[10:11], vcc
	s_cbranch_execz .LBB0_326
	s_bcnt1_i32_b64 s3, s[8:9]
	v_mov_b32_e32 v0, 0x2000
	v_mov_b32_e32 v1, s3
.LBB0_326:
	s_or_b64 exec, exec, s[10:11]
	s_waitcnt vmcnt(0)

.LBB0_428:
	s_or_b64 exec, exec, s[8:9]
	s_mov_b64 s[8:9], exec
	v_mbcnt_lo_u32_b32 v0, s8, 0
	v_mbcnt_hi_u32_b32 v0, s9, v0
	v_cmp_eq_u32_e32 vcc, 0, v0
	s_waitcnt vmcnt(0)
	buffer_inv sc1
	s_and_saveexec_b64 s[10:11], vcc
	s_cbranch_execz .LBB0_430
	s_bcnt1_i32_b64 s3, s[8:9]
	v_mov_b32_e32 v0, 0x2000
	v_mov_b32_e32 v1, s3
.LBB0_430:
	s_or_b64 exec, exec, s[10:11]
	s_waitcnt vmcnt(0)

.LBB0_511:
	s_or_b64 exec, exec, s[10:11]
	v_cvt_f32_u32_e32 v4, v2
	s_waitcnt vmcnt(0)
	v_readfirstlane_b32 s3, v3
	v_sub_u32_e32 v3, 0, v2
	v_rcp_iflag_f32_e32 v4, v4
	v_add_u32_e32 v5, s3, v1
	v_mul_f32_e32 v4, 0x4f7ffffe, v4
	v_cvt_u32_f32_e32 v4, v4
	v_mul_lo_u32 v1, v3, v4
	v_mul_hi_u32 v1, v4, v1
	v_add_u32_e32 v1, v4, v1
	v_mul_hi_u32 v1, v5, v1
	v_mul_lo_u32 v3, v1, v2
	v_sub_u32_e32 v3, v5, v3
	v_add_u32_e32 v4, 1, v1
	v_cmp_ge_u32_e32 vcc, v3, v2
	s_nop 1
	v_cndmask_b32_e32 v1, v1, v4, vcc
	v_sub_u32_e32 v4, v3, v2
	v_cndmask_b32_e32 v3, v3, v4, vcc
	v_add_u32_e32 v4, 1, v1
	v_cmp_ge_u32_e32 vcc, v3, v2
	v_add_u32_e32 v3, 1, v5
	s_nop 0
	v_cndmask_b32_e32 v1, v1, v4, vcc
	v_mul_lo_u32 v4, v2, v1
	v_add_u32_e32 v2, v4, v2
	v_cmp_ne_u32_e32 vcc, v3, v2
	s_and_saveexec_b64 s[8:9], vcc
	s_xor_b64 s[8:9], exec, s[8:9]
	s_cbranch_execz .LBB0_525
	s_waitcnt lgkmcnt(0)
	v_mov_b32_e32 v0, 0x7000
	global_load_dword v0, v0, s[22:23] offset:1280 sc1
	s_add_u32 s38, s22, 0x7500
	s_addc_u32 s39, s23, 0
	s_waitcnt vmcnt(0)
	v_cmp_eq_u32_e32 vcc, v0, v1
	s_and_saveexec_b64 s[10:11], vcc
	s_cbranch_execz .LBB0_524
	s_add_u32 s14, s22, 0x4200
	s_addc_u32 s15, s23, 0
	s_mov_b32 s3, 1
	s_mov_b64 s[42:43], 0
	v_mov_b32_e32 v0, 0
	s_branch .LBB0_515

.LBB0_542:
	s_or_b64 exec, exec, s[8:9]
	s_mov_b64 s[8:9], exec
	v_mbcnt_lo_u32_b32 v0, s8, 0
	v_mbcnt_hi_u32_b32 v0, s9, v0
	v_cmp_eq_u32_e32 vcc, 0, v0
	s_waitcnt vmcnt(0)
	buffer_inv sc1
	s_and_saveexec_b64 s[10:11], vcc
	s_cbranch_execz .LBB0_544
	s_bcnt1_i32_b64 s3, s[8:9]
	v_mov_b32_e32 v0, 0x2000
	v_mov_b32_e32 v1, s3
.LBB0_544:
	s_or_b64 exec, exec, s[10:11]
	s_waitcnt vmcnt(0)

.LBB0_596:
	s_or_b64 exec, exec, s[10:11]
	v_cvt_f32_u32_e32 v4, v2
	s_waitcnt vmcnt(0)
	v_readfirstlane_b32 s3, v3
	v_sub_u32_e32 v3, 0, v2
	v_rcp_iflag_f32_e32 v4, v4
	v_add_u32_e32 v5, s3, v1
	v_mul_f32_e32 v4, 0x4f7ffffe, v4
	v_cvt_u32_f32_e32 v4, v4
	v_mul_lo_u32 v1, v3, v4
	v_mul_hi_u32 v1, v4, v1
	v_add_u32_e32 v1, v4, v1
	v_mul_hi_u32 v1, v5, v1
	v_mul_lo_u32 v3, v1, v2
	v_sub_u32_e32 v3, v5, v3
	v_add_u32_e32 v4, 1, v1
	v_cmp_ge_u32_e32 vcc, v3, v2
	s_nop 1
	v_cndmask_b32_e32 v1, v1, v4, vcc
	v_sub_u32_e32 v4, v3, v2
	v_cndmask_b32_e32 v3, v3, v4, vcc
	v_add_u32_e32 v4, 1, v1
	v_cmp_ge_u32_e32 vcc, v3, v2
	v_add_u32_e32 v3, 1, v5
	s_nop 0
	v_cndmask_b32_e32 v1, v1, v4, vcc
	v_mul_lo_u32 v4, v2, v1
	v_add_u32_e32 v2, v4, v2
	v_cmp_ne_u32_e32 vcc, v3, v2
	s_and_saveexec_b64 s[8:9], vcc
	s_xor_b64 s[8:9], exec, s[8:9]
	s_cbranch_execz .LBB0_610
	s_waitcnt lgkmcnt(0)
	v_mov_b32_e32 v0, 0x7000
	global_load_dword v0, v0, s[22:23] offset:1280 sc1
	s_add_u32 s44, s22, 0x7500
	s_addc_u32 s45, s23, 0
	s_waitcnt vmcnt(0)
	v_cmp_eq_u32_e32 vcc, v0, v1
	s_and_saveexec_b64 s[10:11], vcc
	s_cbranch_execz .LBB0_609
	s_add_u32 s14, s22, 0x4200
	s_addc_u32 s15, s23, 0
	s_mov_b32 s3, 1
	s_mov_b64 s[46:47], 0
	v_mov_b32_e32 v0, 0
	s_branch .LBB0_600

.LBB0_627:
	s_or_b64 exec, exec, s[8:9]
	s_mov_b64 s[8:9], exec
	v_mbcnt_lo_u32_b32 v0, s8, 0
	v_mbcnt_hi_u32_b32 v0, s9, v0
	v_cmp_eq_u32_e32 vcc, 0, v0
	s_waitcnt vmcnt(0)
	buffer_inv sc1
	s_and_saveexec_b64 s[10:11], vcc
	s_cbranch_execz .LBB0_629
	s_bcnt1_i32_b64 s3, s[8:9]
	v_mov_b32_e32 v0, 0x2000
	v_mov_b32_e32 v1, s3
.LBB0_629:
	s_or_b64 exec, exec, s[10:11]
	s_waitcnt vmcnt(0)

.LBB0_680:
	s_or_b64 exec, exec, s[12:13]
	v_cvt_f32_u32_e32 v4, v2
	s_waitcnt vmcnt(0)
	v_readfirstlane_b32 s3, v3
	v_sub_u32_e32 v3, 0, v2
	v_rcp_iflag_f32_e32 v4, v4
	v_add_u32_e32 v5, s3, v1
	v_mul_f32_e32 v4, 0x4f7ffffe, v4
	v_cvt_u32_f32_e32 v4, v4
	v_mul_lo_u32 v1, v3, v4
	v_mul_hi_u32 v1, v4, v1
	v_add_u32_e32 v1, v4, v1
	v_mul_hi_u32 v1, v5, v1
	v_mul_lo_u32 v3, v1, v2
	v_sub_u32_e32 v3, v5, v3
	v_add_u32_e32 v4, 1, v1
	v_cmp_ge_u32_e32 vcc, v3, v2
	s_nop 1
	v_cndmask_b32_e32 v1, v1, v4, vcc
	v_sub_u32_e32 v4, v3, v2
	v_cndmask_b32_e32 v3, v3, v4, vcc
	v_add_u32_e32 v4, 1, v1
	v_cmp_ge_u32_e32 vcc, v3, v2
	v_add_u32_e32 v3, 1, v5
	s_nop 0
	v_cndmask_b32_e32 v1, v1, v4, vcc
	v_mul_lo_u32 v4, v2, v1
	v_add_u32_e32 v2, v4, v2
	v_cmp_ne_u32_e32 vcc, v3, v2
	s_and_saveexec_b64 s[10:11], vcc
	s_xor_b64 s[10:11], exec, s[10:11]
	s_cbranch_execz .LBB0_694
	s_waitcnt lgkmcnt(0)
	v_mov_b32_e32 v0, 0x7000
	global_load_dword v0, v0, s[22:23] offset:1280 sc1
	s_add_u32 s44, s22, 0x7500
	s_addc_u32 s45, s23, 0
	s_waitcnt vmcnt(0)
	v_cmp_eq_u32_e32 vcc, v0, v1
	s_and_saveexec_b64 s[12:13], vcc
	s_cbranch_execz .LBB0_693
	s_add_u32 s14, s22, 0x4200
	s_addc_u32 s15, s23, 0
	s_mov_b32 s3, 1
	s_mov_b64 s[46:47], 0
	v_mov_b32_e32 v0, 0
	s_branch .LBB0_684

.LBB0_711:
	s_or_b64 exec, exec, s[10:11]
	s_mov_b64 s[10:11], exec
	v_mbcnt_lo_u32_b32 v0, s10, 0
	v_mbcnt_hi_u32_b32 v0, s11, v0
	v_cmp_eq_u32_e32 vcc, 0, v0
	s_waitcnt vmcnt(0)
	buffer_inv sc1
	s_and_saveexec_b64 s[12:13], vcc
	s_cbranch_execz .LBB0_713
	s_bcnt1_i32_b64 s3, s[10:11]
	v_mov_b32_e32 v0, 0x2000
	v_mov_b32_e32 v1, s3
.LBB0_713:
	s_or_b64 exec, exec, s[12:13]
	s_waitcnt vmcnt(0)

.LBB0_796:
	s_or_b64 exec, exec, s[10:11]
	s_mov_b64 s[10:11], exec
	v_mbcnt_lo_u32_b32 v0, s10, 0
	v_mbcnt_hi_u32_b32 v0, s11, v0
	v_cmp_eq_u32_e32 vcc, 0, v0
	s_waitcnt vmcnt(0)
	buffer_inv sc1
	s_and_saveexec_b64 s[12:13], vcc
	s_cbranch_execz .LBB0_798
	s_bcnt1_i32_b64 s3, s[10:11]
	v_mov_b32_e32 v0, 0x2000
	v_mov_b32_e32 v1, s3
.LBB0_798:
	s_or_b64 exec, exec, s[12:13]
	s_waitcnt vmcnt(0)

.LBB0_938:
	s_or_b64 exec, exec, s[10:11]
	s_mov_b64 s[10:11], exec
	v_mbcnt_lo_u32_b32 v0, s10, 0
	v_mbcnt_hi_u32_b32 v0, s11, v0
	v_cmp_eq_u32_e32 vcc, 0, v0
	s_waitcnt vmcnt(0)
	buffer_inv sc1
	s_and_saveexec_b64 s[12:13], vcc
	s_cbranch_execz .LBB0_940
	s_bcnt1_i32_b64 s3, s[10:11]
	v_mov_b32_e32 v0, 0x2000
	v_mov_b32_e32 v1, s3
.LBB0_940:
	s_or_b64 exec, exec, s[12:13]
	s_waitcnt vmcnt(0)

.LBB0_1023:
	s_or_b64 exec, exec, s[10:11]
	s_mov_b64 s[10:11], exec
	v_mbcnt_lo_u32_b32 v0, s10, 0
	v_mbcnt_hi_u32_b32 v0, s11, v0
	v_cmp_eq_u32_e32 vcc, 0, v0
	s_waitcnt vmcnt(0)
	buffer_inv sc1
	s_and_saveexec_b64 s[12:13], vcc
	s_cbranch_execz .LBB0_1025
	s_bcnt1_i32_b64 s3, s[10:11]
	v_mov_b32_e32 v0, 0x2000
	v_mov_b32_e32 v1, s3
.LBB0_1025:
	s_or_b64 exec, exec, s[12:13]
	s_waitcnt vmcnt(0)

.LBB0_1091:
	s_or_b64 exec, exec, s[10:11]
	s_mov_b64 s[10:11], exec
	v_mbcnt_lo_u32_b32 v0, s10, 0
	v_mbcnt_hi_u32_b32 v0, s11, v0
	v_cmp_eq_u32_e32 vcc, 0, v0
	s_waitcnt vmcnt(0)
	buffer_inv sc1
	s_and_saveexec_b64 s[12:13], vcc
	s_cbranch_execz .LBB0_1093
	s_bcnt1_i32_b64 s3, s[10:11]
	v_mov_b32_e32 v0, 0x2000
	v_mov_b32_e32 v1, s3
.LBB0_1093:
	s_or_b64 exec, exec, s[12:13]
	s_waitcnt vmcnt(0)

.LBB0_1172:
	s_or_b64 exec, exec, s[12:13]
	v_cvt_f32_u32_e32 v4, v2
	s_waitcnt vmcnt(0)
	v_readfirstlane_b32 s3, v3
	v_sub_u32_e32 v3, 0, v2
	v_rcp_iflag_f32_e32 v4, v4
	v_add_u32_e32 v5, s3, v1
	v_mul_f32_e32 v4, 0x4f7ffffe, v4
	v_cvt_u32_f32_e32 v4, v4
	v_mul_lo_u32 v1, v3, v4
	v_mul_hi_u32 v1, v4, v1
	v_add_u32_e32 v1, v4, v1
	v_mul_hi_u32 v1, v5, v1
	v_mul_lo_u32 v3, v1, v2
	v_sub_u32_e32 v3, v5, v3
	v_add_u32_e32 v4, 1, v1
	v_cmp_ge_u32_e32 vcc, v3, v2
	s_nop 1
	v_cndmask_b32_e32 v1, v1, v4, vcc
	v_sub_u32_e32 v4, v3, v2
	v_cndmask_b32_e32 v3, v3, v4, vcc
	v_add_u32_e32 v4, 1, v1
	v_cmp_ge_u32_e32 vcc, v3, v2
	v_add_u32_e32 v3, 1, v5
	s_nop 0
	v_cndmask_b32_e32 v1, v1, v4, vcc
	v_mul_lo_u32 v4, v2, v1
	v_add_u32_e32 v2, v4, v2
	v_cmp_ne_u32_e32 vcc, v3, v2
	s_and_saveexec_b64 s[10:11], vcc
	s_xor_b64 s[10:11], exec, s[10:11]
	s_cbranch_execz .LBB0_1186
	s_waitcnt lgkmcnt(0)
	v_mov_b32_e32 v0, 0x7000
	global_load_dword v0, v0, s[22:23] offset:1280 sc1
	s_add_u32 s36, s22, 0x7500
	s_addc_u32 s37, s23, 0
	s_waitcnt vmcnt(0)
	v_cmp_eq_u32_e32 vcc, v0, v1
	s_and_saveexec_b64 s[12:13], vcc
	s_cbranch_execz .LBB0_1185
	s_add_u32 s14, s22, 0x4200
	s_addc_u32 s15, s23, 0
	s_mov_b32 s3, 1
	s_mov_b64 s[44:45], 0
	v_mov_b32_e32 v0, 0
	s_branch .LBB0_1176

.LBB0_1203:
	s_or_b64 exec, exec, s[10:11]
	s_mov_b64 s[10:11], exec
	v_mbcnt_lo_u32_b32 v0, s10, 0
	v_mbcnt_hi_u32_b32 v0, s11, v0
	v_cmp_eq_u32_e32 vcc, 0, v0
	s_waitcnt vmcnt(0)
	buffer_inv sc1
	s_and_saveexec_b64 s[12:13], vcc
	s_cbranch_execz .LBB0_1205
	s_bcnt1_i32_b64 s3, s[10:11]
	v_mov_b32_e32 v0, 0x2000
	v_mov_b32_e32 v1, s3
.LBB0_1205:
	s_or_b64 exec, exec, s[12:13]
	s_waitcnt vmcnt(0)

.LBB0_1257:
	s_or_b64 exec, exec, s[10:11]
	v_cvt_f32_u32_e32 v4, v2
	s_waitcnt vmcnt(0)
	v_readfirstlane_b32 s8, v3
	v_sub_u32_e32 v3, 0, v2
	v_rcp_iflag_f32_e32 v4, v4
	v_add_u32_e32 v5, s8, v1
	v_mul_f32_e32 v4, 0x4f7ffffe, v4
	v_cvt_u32_f32_e32 v4, v4
	v_mul_lo_u32 v1, v3, v4
	v_mul_hi_u32 v1, v4, v1
	v_add_u32_e32 v1, v4, v1
	v_mul_hi_u32 v1, v5, v1
	v_mul_lo_u32 v3, v1, v2
	v_sub_u32_e32 v3, v5, v3
	v_add_u32_e32 v4, 1, v1
	v_cmp_ge_u32_e32 vcc, v3, v2
	s_nop 1
	v_cndmask_b32_e32 v1, v1, v4, vcc
	v_sub_u32_e32 v4, v3, v2
	v_cndmask_b32_e32 v3, v3, v4, vcc
	v_add_u32_e32 v4, 1, v1
	v_cmp_ge_u32_e32 vcc, v3, v2
	v_add_u32_e32 v3, 1, v5
	s_nop 0
	v_cndmask_b32_e32 v1, v1, v4, vcc
	v_mul_lo_u32 v4, v2, v1
	v_add_u32_e32 v2, v4, v2
	v_cmp_ne_u32_e32 vcc, v3, v2
	s_and_saveexec_b64 s[8:9], vcc
	s_xor_b64 s[8:9], exec, s[8:9]
	s_cbranch_execz .LBB0_1271
	s_waitcnt lgkmcnt(0)
	v_mov_b32_e32 v0, 0x7000
	global_load_dword v0, v0, s[22:23] offset:1280 sc1
	s_add_u32 s14, s22, 0x7500
	s_addc_u32 s15, s23, 0
	s_waitcnt vmcnt(0)
	v_cmp_eq_u32_e32 vcc, v0, v1
	s_and_saveexec_b64 s[10:11], vcc
	s_cbranch_execz .LBB0_1270
	s_add_u32 s12, s22, 0x4200
	s_addc_u32 s13, s23, 0
	s_mov_b32 s19, 1
	s_mov_b64 s[16:17], 0
	v_mov_b32_e32 v0, 0
	s_branch .LBB0_1261

.LBB0_1288:
	s_or_b64 exec, exec, s[8:9]
	s_mov_b64 s[8:9], exec
	v_mbcnt_lo_u32_b32 v0, s8, 0
	v_mbcnt_hi_u32_b32 v0, s9, v0
	v_cmp_eq_u32_e32 vcc, 0, v0
	s_waitcnt vmcnt(0)
	buffer_inv sc1
	s_and_saveexec_b64 s[10:11], vcc
	s_cbranch_execz .LBB0_1290
	s_bcnt1_i32_b64 s8, s[8:9]
	v_mov_b32_e32 v0, 0x2000
	v_mov_b32_e32 v1, s8
.LBB0_1290:
	s_or_b64 exec, exec, s[10:11]
	s_waitcnt vmcnt(0)
